# stack7 plus one static s_setprio 1 for waves 0-3 (the other half than tried before) during the attention phase
# baseline (speedup 1.0000x reference)
; #define SBAR() __builtin_amdgcn_sched_barrier(0)
; #define VMW() asm volatile("s_waitcnt vmcnt(0)" ::: "memory")
; #define SLOAD_H(Kp, Vp, k0) do { S.st_v0 = load8<TIn>(ROW(Vp, k0, sr)); S.st_v1 = load8<TIn>(ROW(Vp, k0, 32 + sr));              \
;                          S.st_k0 = load8<TIn>(ROW(Kp, k0, sr)); S.st_k1 = load8<TIn>(ROW(Kp, k0, 32 + sr)); } while (0)
; #define SWRITE_HK(bf) do { *(bf16x8*)(K_lds + (bf) * SHM_K + kws) = S.st_k0; *(bf16x8*)(K_lds + (bf) * SHM_K + kws + 32 * 256) = S.st_k1; } while (0)
; #define SLOAD_F(p, k0) do { S.sf0 = *(const f32x4*)ROW(p, k0, sr); S.sf1 = *(const f32x4*)(ROW(p, k0, sr) + 4);                \
;                             S.sf2 = *(const f32x4*)ROW(p, k0, 32 + sr); S.sf3 = *(const f32x4*)(ROW(p, k0, 32 + sr) + 4); } while (0)
; #define SWRITE_KF(bf) do { *(bf16x8*)(K_lds + (bf) * SHM_K + kws) = pack8(S.sf0, S.sf1); *(bf16x8*)(K_lds + (bf) * SHM_K + kws + 32 * 256) = pack8(S.sf2, S.sf3); } while (0)
; template <class TIn, class TOut>
; __device__ __forceinline__ void causal_swa_prime(const BlockRef<TIn, TOut>& cur, int W, char* lds, Seam<TIn>& S) {
;     constexpr bool F32 = same_t<TIn, float>::v;
;     int tid_l_ = threadIdx.x; asm volatile("" : "+v"(tid_l_)); const int tid = tid_l_, wid = __builtin_amdgcn_readfirstlane(tid >> 6), lane = tid & 63, r32 = lane & 31, hi = lane >> 5;
;     const int sr = tid >> 4, sc = (tid & 15) * 8, kws = KSWZ(sr, sc * 2); char* K_lds = lds + 2 * SHM_V;
;     const int kb0 = swa_jlo(cur.P0, W) * KVBLK;
;     for (int d0 = 0; d0 < 8; ++d0) S.qr[d0] = load8<TIn>(cur.Q + (unsigned)((wid * QBLK + r32) * LD + d0 * 16 + hi * 8));
;     if constexpr (F32) { SLOAD_F((const float*)cur.K, kb0); VMW(); SWRITE_KF(0); SBAR(); SLOAD_F((const float*)cur.V, kb0); }
;     else { SLOAD_H(cur.K, cur.V, kb0); VMW(); SWRITE_HK(0); }
;     __syncthreads();
; }
; __device__ __forceinline__ void attention_phase(char* lds, const bf16_t* Q, const bf16_t* K, const bf16_t* V, bf16_t* O1, bf16_t* O2, bf16_t* OC, const float* lamv, const float* subln, int G, int bid) {
;     constexpr int total = 256, W = 1 << 30;
;     for (int L = bid; L < total; L += G) {
;         ABlock cur = att_ref(L, 0, Q, K, V, O1, O2);
;         att::Seam<att::bf16> S; S.mk = 0.f; S.lk = 0.f; S.fx = false;
;         att::causal_swa_prime<att::bf16, att::bf16>(cur, W, lds, S);
.LBB0_493:
	s_andn2_b64 vcc, exec, s[8:9]
	s_cbranch_vccnz .LBB0_685
	s_cmp_eq_u32 s22, 2
	s_cbranch_scc0 .LBB0_685
	s_cmpk_gt_i32 s23, 0xff
	s_cbranch_scc1 .LBB0_685
	s_add_u32 s6, s4, 0x12100000
	s_load_dwordx4 s[44:47], s[64:65], 0x58
	s_addc_u32 s7, s5, 0
	s_add_u32 s8, s4, 0x16100000
	s_addc_u32 s9, s5, 0
	s_add_u32 s12, s4, 0x1a100000
	s_addc_u32 s13, s5, 0
	s_mov_b32 s10, s23
	v_readfirstlane_b32 s2, v208
	s_nop 3
	s_cmpk_lt_u32 s2, 0x100
	s_cbranch_scc0 .Lattprio_skip
	s_setprio 1
.Lattprio_skip:
.LBB0_497:
	s_ashr_i32 s18, s10, 5
	s_lshl_b32 s2, s10, 8
	s_ashr_i32 s19, s18, 31
	s_and_b32 s17, s2, 0x300
	s_lshl_b64 s[30:31], s[18:19], 22
	s_lshl_b32 s2, s17, 11
	s_or_b32 s26, s30, s2
	s_mov_b32 s27, s31
	s_lshl_b64 s[34:35], s[26:27], 1
	s_add_u32 s2, s56, s34
	s_addc_u32 s27, s57, s35
	s_lshl_b32 s26, s10, 6
	s_and_b32 s26, s26, 0x700
	s_lshl_b32 s29, s26, 1
	s_add_u32 s66, s2, s29
	s_addc_u32 s67, s27, 0
	s_lshl_b64 s[40:41], s[18:19], 23
	s_add_u32 s27, s60, s40
	s_addc_u32 s28, s61, s41
	s_add_u32 s86, s27, s29
	s_addc_u32 s87, s28, 0
	s_add_u32 s2, s6, s40
	s_addc_u32 s33, s7, s41
	s_add_u32 s62, s2, s29
	s_addc_u32 s63, s33, 0
	s_add_u32 s2, s8, s34
	s_addc_u32 s33, s9, s35
	s_waitcnt vmcnt(0)
	v_mov_b32_e32 v2, v208
	s_add_u32 s74, s2, s29
	s_addc_u32 s75, s33, 0
	v_readfirstlane_b32 s2, v2
	s_lshr_b32 s2, s2, 1
	s_and_b32 s2, s2, 0x1fffe0
	v_lshrrev_b32_e32 v1, 2, v2
	v_and_or_b32 v0, v2, 31, s2
	v_and_b32_e32 v1, 8, v1
	v_lshl_or_b32 v128, v0, 11, v1
	v_lshl_add_u64 v[0:1], v[128:129], 1, s[66:67]
	global_load_dwordx4 v[158:161], v[0:1], off
	global_load_dwordx4 v[154:157], v[0:1], off offset:32
	global_load_dwordx4 v[150:153], v[0:1], off offset:64
	global_load_dwordx4 v[146:149], v[0:1], off offset:96
	global_load_dwordx4 v[142:145], v[0:1], off offset:128
	global_load_dwordx4 v[138:141], v[0:1], off offset:160
	global_load_dwordx4 v[134:137], v[0:1], off offset:192
	global_load_dwordx4 v[130:133], v[0:1], off offset:224
	v_lshlrev_b32_e32 v1, 3, v2
	v_ashrrev_i32_e32 v0, 4, v2
	v_and_b32_e32 v1, 0x78, v1
	v_lshl_or_b32 v128, v0, 11, v1
	v_lshlrev_b32_e32 v8, 8, v0
	v_lshlrev_b32_e32 v3, 1, v1
	s_movk_i32 s2, 0x70
	v_lshlrev_b64 v[0:1], 1, v[128:129]
	v_add_u32_e32 v128, 0x10000, v128
	v_bitop3_b32 v9, v3, v2, s2 bitop3:0x78
	v_lshl_add_u64 v[2:3], s[62:63], 0, v[0:1]
	v_lshlrev_b64 v[4:5], 1, v[128:129]
	global_load_dwordx4 v[112:115], v[2:3], off
	v_lshl_add_u64 v[2:3], s[62:63], 0, v[4:5]
	v_lshl_add_u64 v[0:1], s[86:87], 0, v[0:1]
	global_load_dwordx4 v[116:119], v[2:3], off
	v_lshl_add_u64 v[4:5], s[86:87], 0, v[4:5]
	global_load_dwordx4 v[0:3], v[0:1], off
	v_add3_u32 v8, 0, v8, v9
	global_load_dwordx4 v[4:7], v[4:5], off
	s_waitcnt vmcnt(0)
	s_xor_b32 s49, s17, 0x700
	v_mov_b32_e32 v80, 0
	s_mov_b32 s29, 0
	v_mov_b32_e32 v220, 0
	s_mov_b32 s2, s17
	s_mov_b64 s[88:89], s[62:63]
	s_mov_b32 s37, s17
	s_mov_b64 s[68:69], s[74:75]
	s_mov_b64 s[70:71], s[62:63]
	s_mov_b64 s[72:73], s[86:87]
	s_waitcnt vmcnt(1)
	ds_write_b128 v8, v[0:3] offset:32768
	s_waitcnt vmcnt(0)
	ds_write_b128 v8, v[4:7] offset:40960
	s_waitcnt lgkmcnt(0)
	s_barrier
	s_branch .LBB0_499

; __global__ void __launch_bounds__(512, 2) fwd_megakernel(Args a) {
;     ...
;         case 2: if (!PON(2)) break; attention_phase((char*)lds_raw, WSB(WS_T1), WSB(WS_T2), WSB(WS_T3), WSB(WS_T4), WSB(WS_T5), WSB(WS_T0), ap->in[11], ap->in[12], G, bid); break;
.LBB0_685:
	s_setprio 0
	s_mov_b64 s[8:9], 0
